# v47 + prompt attention epilogue: 16 dwordx2 stores per lane paired into 8 dwordx4 via v_permlane32_swap
# baseline (speedup 1.0000x reference)
; __device__ __forceinline__ unsigned cvtpk(float lo, float hi) { f32x2_t v = {lo, hi}; bf16x2_t b = __builtin_convertvector(v, bf16x2_t); return __builtin_bit_cast(unsigned, b); }
; __device__ __forceinline__ void attn_mfma_phase(LAS unsigned char* lds, const bf16* QKVb, bf16* OPART, float2* ML, int tid, int wave, int lane) {
;     ...
;         const float lt = l + __shfl_xor(l, 32), inv = 1.f / lt;
;         bf16* op = OPART + ((size_t)b * MP + tok_q) * 512 + h * 64 + 4 * hh;
; #pragma unroll
;         for (int g = 0; g < 4; ++g) {
;             *(uint2*)(op + 8 * g) = make_uint2(cvtpk(o0[4 * g] * inv, o0[4 * g + 1] * inv), cvtpk(o0[4 * g + 2] * inv, o0[4 * g + 3] * inv));
;             *(uint2*)(op + 32 + 8 * g) = make_uint2(cvtpk(o1[4 * g] * inv, o1[4 * g + 1] * inv), cvtpk(o1[4 * g + 2] * inv, o1[4 * g + 3] * inv));
;         }
;         if (hh == 0) ML[((size_t)b * MP + tok_q) * 8 + h] = make_float2(m, lt);
.LBB0_1052:
	ds_bpermute_b32 v35, v154, v34
	s_lshl_b32 s33, s1, 24
	v_mov_b32_e32 v147, v143
	v_readlane_b32 s87, v254, 12
	s_waitcnt lgkmcnt(0)
	v_add_f32_e32 v51, v34, v35
	v_div_scale_f32 v34, s[70:71], v51, v51, 1.0
	v_rcp_f32_e32 v35, v34
	s_add_u32 s70, s74, s33
	s_addc_u32 s71, s75, 0
	v_fma_f32 v36, -v34, v35, 1.0
	v_fmac_f32_e32 v35, v36, v35
	v_div_scale_f32 v36, vcc, 1.0, v51, 1.0
	v_mul_f32_e32 v37, v36, v35
	v_fma_f32 v38, -v34, v37, v36
	v_fmac_f32_e32 v37, v38, v35
	v_fma_f32 v34, -v34, v37, v36
	v_div_fmas_f32 v34, v34, v35, v37
	v_lshlrev_b64 v[36:37], 10, v[148:149]
	v_div_fixup_f32 v34, v34, v51, 1.0
	v_lshl_add_u64 v[36:37], s[70:71], 0, v[36:37]
	v_lshl_add_u64 v[36:37], s[94:95], 1, v[36:37]
	v_lshl_add_u64 v[36:37], v[36:37], 0, v[146:147]
	v_lshl_add_u64 v[36:37], v[36:37], 0, v[146:147]
	v_pk_mul_f32 v[2:3], v[2:3], v[34:35] op_sel_hi:[1,0]
	v_pk_mul_f32 v[4:5], v[4:5], v[34:35] op_sel_hi:[1,0]
	v_pk_mul_f32 v[40:41], v[6:7], v[34:35] op_sel_hi:[1,0]
	v_pk_mul_f32 v[42:43], v[8:9], v[34:35] op_sel_hi:[1,0]
	v_cvt_pk_bf16_f32 v2, v2, v3
	v_cvt_pk_bf16_f32 v3, v4, v5
	v_cvt_pk_bf16_f32 v4, v40, v41
	v_cvt_pk_bf16_f32 v5, v42, v43
	s_nop 1
	v_permlane32_swap_b32_e32 v2, v4
	v_permlane32_swap_b32_e32 v3, v5
	global_store_dwordx4 v[36:37], v[2:5], off
	s_nop 1
	v_pk_mul_f32 v[2:3], v[18:19], v[34:35] op_sel_hi:[1,0]
	v_pk_mul_f32 v[4:5], v[20:21], v[34:35] op_sel_hi:[1,0]
	v_pk_mul_f32 v[40:41], v[22:23], v[34:35] op_sel_hi:[1,0]
	v_pk_mul_f32 v[42:43], v[24:25], v[34:35] op_sel_hi:[1,0]
	v_cvt_pk_bf16_f32 v2, v2, v3
	v_cvt_pk_bf16_f32 v3, v4, v5
	v_cvt_pk_bf16_f32 v4, v40, v41
	v_cvt_pk_bf16_f32 v5, v42, v43
	s_nop 1
	v_permlane32_swap_b32_e32 v2, v4
	v_permlane32_swap_b32_e32 v3, v5
	global_store_dwordx4 v[36:37], v[2:5], off offset:64
	s_nop 1
	v_pk_mul_f32 v[2:3], v[10:11], v[34:35] op_sel_hi:[1,0]
	v_pk_mul_f32 v[4:5], v[12:13], v[34:35] op_sel_hi:[1,0]
	v_pk_mul_f32 v[40:41], v[14:15], v[34:35] op_sel_hi:[1,0]
	v_pk_mul_f32 v[42:43], v[16:17], v[34:35] op_sel_hi:[1,0]
	v_cvt_pk_bf16_f32 v2, v2, v3
	v_cvt_pk_bf16_f32 v3, v4, v5
	v_cvt_pk_bf16_f32 v4, v40, v41
	v_cvt_pk_bf16_f32 v5, v42, v43
	s_nop 1
	v_permlane32_swap_b32_e32 v2, v4
	v_permlane32_swap_b32_e32 v3, v5
	global_store_dwordx4 v[36:37], v[2:5], off offset:32
	s_nop 1
	v_pk_mul_f32 v[2:3], v[26:27], v[34:35] op_sel_hi:[1,0]
	v_pk_mul_f32 v[4:5], v[28:29], v[34:35] op_sel_hi:[1,0]
	v_pk_mul_f32 v[40:41], v[30:31], v[34:35] op_sel_hi:[1,0]
	v_pk_mul_f32 v[42:43], v[32:33], v[34:35] op_sel_hi:[1,0]
	v_cvt_pk_bf16_f32 v2, v2, v3
	v_cvt_pk_bf16_f32 v3, v4, v5
	v_cvt_pk_bf16_f32 v4, v40, v41
	v_cvt_pk_bf16_f32 v5, v42, v43
	s_nop 1
	v_permlane32_swap_b32_e32 v2, v4
	v_permlane32_swap_b32_e32 v3, v5
	global_store_dwordx4 v[36:37], v[2:5], off offset:96
	s_nop 1
	s_and_saveexec_b64 s[94:95], s[4:5]
	s_cbranch_execz .LBB0_1010
	s_lshl_b32 s1, s1, 20
	v_readlane_b32 s70, v255, 5
	v_readlane_b32 s71, v255, 6
	s_add_u32 s70, s70, s1
	s_addc_u32 s71, s71, 0
	v_lshlrev_b64 v[2:3], 6, v[148:149]
	v_lshl_add_u64 v[2:3], s[70:71], 0, v[2:3]
	s_ashr_i32 s1, s0, 31
	v_lshl_add_u64 v[2:3], s[0:1], 3, v[2:3]
	global_store_dwordx2 v[2:3], v[50:51], off
	s_branch .LBB0_1010
